# mix part 2: odd workgroups take their second-round item (gMLP / context DFT) before their latent position-DFT item, halving the number of concurrent bandwidth-heavy DFT tiles
# baseline (speedup 1.0000x reference)
; DI int otid() { int t = threadIdx.x; asm volatile("" : "+v"(t)); return t; }
; DI void phase_mix(KP p, int l, char* lds) {
;     ...
;   const int xcd = blockIdx.x & 7, lb = 2 * (blockIdx.x >> 3) + __builtin_amdgcn_readfirstlane(otid() >> 8), nlb = 2 * (gridDim.x >> 3);
;   const int nDL = 64, nA = 0, nB = 0, nDC = upd ? 8 : 0, nAc = 0, nBc = 0, nCM = 72, nFN = upd ? 72 : 64;
;   const int e0 = nDL, e1 = e0 + nA, e2 = e1 + nB, e3 = e2 + nDC, e4 = e3 + nAc, e5 = e4 + nBc, e6 = e5 + nCM, e7 = e6 + nFN;
;   unsigned* cnt = (unsigned*)(ws + WS_CNT) + l * 288;
;   const bf16_t* wf = (const bf16_t*)(ws + WS_WF) + (size_t)l * 256 * 256;
;   {
;     const int lbw = blockIdx.x >> 3, nlbw = gridDim.x >> 3;
;     const int nW = upd ? 144 : 128;
;     for (int it = lbw; it < nW; it += nlbw) {
;       const bool isA = (it < 64) || (it >= 128 && it < 136);
;       int b, hd, q0, k0, nk;
;       if (it < 128) { const int i2 = it & 63; b = 2 * xcd + (i2 >> 5); hd = (i2 >> 3) & 3; q0 = (i2 & 7) * 256; k0 = 0; nk = T; }
;       else { const int i2 = (it - 128) & 7; b = 2 * xcd + (i2 >> 2); hd = i2 & 3; q0 = SEQ; k0 = SEQ; nk = CL; }
;       const size_t r0 = (size_t)b * T + q0; const size_t bh = (size_t)b * 4 + hd, bk = (size_t)b * 2 + (hd >> 1);
;       if (isA) {
;         if (sbA <= 30.f) attn_item8<96, true>(QA + (bh * T + q0) * 96, KA + (bh * T + k0) * 96, VAT + bh * 64 * T + k0, nk, lds, P + r0 * NIN + O_GA + 64 * hd, Y + r0 * 1024 + 64 * hd, sbA);
;         else attn_item8<96, false>(QA + (bh * T + q0) * 96, KA + (bh * T + k0) * 96, VAT + bh * 64 * T + k0, nk, lds, P + r0 * NIN + O_GA + 64 * hd, Y + r0 * 1024 + 64 * hd, 0.f);
;       } else {
;         if (sbB <= 30.f) attn_item8<64, true>(QB + (bh * T + q0) * 64, KB + (bk * T + k0) * 64, VBT + bk * 64 * T + k0, nk, lds, P + r0 * NIN + O_GB + 64 * hd, Y + r0 * 1024 + 256 + 64 * hd, sbB);
;         else attn_item8<64, false>(QB + (bh * T + q0) * 64, KB + (bk * T + k0) * 64, VBT + bk * 64 * T + k0, nk, lds, P + r0 * NIN + O_GB + 64 * hd, Y + r0 * 1024 + 256 + 64 * hd, 0.f);
;       }
;     }
;     __syncthreads();
;   }
;   const int tid0 = otid() & 255;
;   for (int it = lb; it < e7; it += nlb) {
.LBB0_123:
	v_readlane_b32 s19, v255, 37
	s_ashr_i32 s2, s19, 8
	v_readlane_b32 s4, v254, 40
	s_add_i32 s46, s2, s4
	s_mov_b32 s101, s46
	v_readlane_b32 s47, v253, 4
	s_nop 1
	s_cmp_lg_u32 s47, 64
	s_cbranch_scc1 .Lswap0_done
	s_bitcmp1_b32 s101, 1
	s_cbranch_scc0 .Lswap0_done
	s_xor_b32 s46, s46, 64
.Lswap0_done:
	v_readlane_b32 s4, v255, 35
	v_readlane_b32 s5, v255, 36
	s_and_b64 s[4:5], s[4:5], exec
	s_cselect_b32 s47, 64, 0x48
	s_add_i32 s45, s47, 0x48
	s_add_i32 s14, s45, s47
	v_mov_b32_e32 v0, v196
	s_cmp_ge_i32 s46, s14
	s_waitcnt lgkmcnt(0)
	s_barrier
	s_cbranch_scc1 .LBB0_180
	v_readlane_b32 s34, v255, 33
	v_readlane_b32 s35, v255, 34
	s_add_u32 s2, s34, 0x14f75100
	v_writelane_b32 v255, s2, 38
	s_addc_u32 s2, s35, 0
	v_writelane_b32 v255, s2, 39
	s_add_u32 s2, s34, 0x1075100
	v_writelane_b32 v255, s2, 47
	s_addc_u32 s2, s35, 0
	v_writelane_b32 v255, s2, 48
	s_add_u32 s2, s34, 0x1875100
	v_writelane_b32 v255, s2, 49
	s_addc_u32 s2, s35, 0
	v_writelane_b32 v255, s2, 50
	s_add_u32 s2, s34, 0x1cd75100
	v_writelane_b32 v255, s2, 51
	s_addc_u32 s2, s35, 0
	v_writelane_b32 v255, s2, 53
	v_cmp_eq_u32_sdwa s[64:65], v0, v1 src0_sel:BYTE_0 src1_sel:DWORD
	v_readlane_b32 s20, v255, 26
	v_readlane_b32 s21, v255, 27
	s_ashr_i32 s21, s20, 31
	s_lshl_b64 s[4:5], s[20:21], 17
	s_add_u32 s2, s34, s4
	s_addc_u32 s18, s35, s5
	s_add_u32 s4, s2, 0x1031100
	v_writelane_b32 v255, s4, 55
	s_addc_u32 s4, s18, 0
	v_writelane_b32 v255, s4, 56
	s_mul_i32 s4, s20, 0x120
	s_ashr_i32 s5, s4, 31
	s_lshl_b64 s[4:5], s[4:5], 2
	s_add_u32 s4, s34, s4
	s_addc_u32 s5, s35, s5
	s_add_u32 s4, s4, 0x1ef88700
	v_writelane_b32 v255, s4, 43
	s_addc_u32 s4, s5, 0
	v_writelane_b32 v255, s4, 44
	s_add_u32 s2, s2, 0xbf1100
	v_writelane_b32 v255, s2, 40
	s_addc_u32 s2, s18, 0
	v_writelane_b32 v255, s2, 41
	s_mov_b32 s2, s20
	v_readlane_b32 s4, v255, 35
	v_readlane_b32 s5, v255, 36
	s_and_b64 s[4:5], s[4:5], exec
	v_writelane_b32 v255, s2, 26
	s_cselect_b32 s44, 16, 18
	s_lshl_b64 s[4:5], s[20:21], 11
	v_writelane_b32 v255, s3, 27
	v_writelane_b32 v255, s4, 57
	s_bfe_u32 s2, s19, 0x10008
	v_cvt_f32_ubyte0_e32 v0, s44
	v_writelane_b32 v255, s5, 58
	s_lshl_b32 s4, s2, 17
	s_add_u32 s4, s34, s4
	v_rcp_iflag_f32_e32 v0, v0
	s_addc_u32 s5, s35, 0
	s_add_u32 s4, s4, 0x14b75100
	v_writelane_b32 v255, s4, 37
	s_addc_u32 s4, s5, 0
	v_writelane_b32 v255, s4, 59
	s_lshl_b32 s4, s2, 19
	v_mul_f32_e32 v0, 0x4f7ffffe, v0
	s_add_u32 s4, s34, s4
	v_cvt_u32_f32_e32 v0, v0
	s_addc_u32 s5, s35, 0
	s_add_u32 s4, s4, 0x13b75100
	v_writelane_b32 v255, s4, 60
	s_addc_u32 s4, s5, 0
	v_writelane_b32 v255, s4, 61
	s_sub_i32 s4, 0, s44
	v_readfirstlane_b32 s5, v0
	s_mul_i32 s4, s4, s5
	s_mul_hi_u32 s4, s5, s4
	s_add_i32 s4, s5, s4
	v_writelane_b32 v255, s4, 42
	s_add_u32 s4, s34, 0x18b5500
	v_writelane_b32 v255, s4, 62
	s_addc_u32 s4, s35, 0
	s_lshl_b32 s2, s2, 8
	v_writelane_b32 v255, s4, 63
	s_add_u32 s4, s34, s2
	s_addc_u32 s5, s35, 0
	v_writelane_b32 v255, s4, 45
	s_nop 1
	v_writelane_b32 v255, s5, 46
	s_branch .LBB0_127

; DI void phase_mix(KP p, int l, char* lds) {
;     ...
;   for (int it = lb; it < e7; it += nlb) {
;     if (it >= e6) {
;       const int i2 = it - e6; const int mpb = upd ? 18 : 16; const int mloc = i2 >> 1, nt = i2 & 1;
.LBB0_126:
	v_readlane_b32 s2, v253, 4
	s_add_i32 s101, s101, s2
	s_mov_b32 s46, s101
	s_cmp_lg_u32 s2, 64
	s_cbranch_scc1 .Lperm_done
	s_cmp_lt_i32 s101, 0x80
	s_cbranch_scc0 .Lswap1_done
	s_bitcmp1_b32 s101, 1
	s_cbranch_scc0 .Lswap1_done
	s_xor_b32 s46, s101, 64
	s_branch .Lperm_done
.Lswap1_done:
	s_cmp_ge_i32 s101, 0x100
	s_cbranch_scc1 .LBB0_180
	s_cmp_lt_i32 s101, 0xc0
	s_cbranch_scc1 .Lperm_done
	s_cmp_lg_u32 s14, 0xc8
	s_cbranch_scc1 .Lperm_l0
	s_sub_i32 s2, s101, 0xc0
	s_mov_b32 s46, 0x7fff
	s_cmp_ge_u32 s2, 4
	s_cbranch_scc0 .Lperm_done
	s_cmp_lt_u32 s2, 8
	s_cbranch_scc0 .Lperm_hi
	s_add_i32 s46, s2, 0xc0
	s_branch .Lperm_done
